# g3: sample s5 + chain S3 16-lane reductions via DPP adds instead of ds_bpermute; chain gated-norm silu gates read before the barrier and computed between the S4 MFMAs, tail rewritten; on top of v9
# speedup vs baseline: 1.0242x; 1.0004x over previous
.LBB0_1073:
	s_or_b64 exec, exec, s[0:1]
	v_lshl_add_u32 v113, v97, 2, 0
	ds_read_b32 v111, v113 offset:47872
	v_add_u32_e32 v104, 0x400, v102
	v_lshlrev_b32_e32 v115, 10, v159
	v_lshlrev_b32_e32 v117, 2, v104
	v_add3_u32 v115, s7, v115, v117
	v_lshl_add_u32 v96, v96, 2, 0
	ds_read_b32 v115, v115
	ds_read_b128 v[160:163], v96 offset:48192
	s_waitcnt lgkmcnt(2)
	v_mul_f32_e32 v111, 0x3fb8aa3b, v111
	v_exp_f32_e32 v117, v111
	ds_read_b128 v[164:167], v96 offset:48208
	v_cmp_eq_u32_e64 s[0:1], 0, v155
	s_waitcnt lgkmcnt(1)
	v_mul_f32_e32 v111, v126, v160
	v_fmac_f32_e32 v111, v117, v115
	v_fmac_f32_e32 v111, v127, v161
	v_fmac_f32_e32 v111, v100, v162
	v_fmac_f32_e32 v111, v101, v163
	s_waitcnt lgkmcnt(0)
	v_fmac_f32_e32 v111, v98, v164
	v_fmac_f32_e32 v111, v99, v165
	v_fmac_f32_e32 v111, v124, v166
	v_fmac_f32_e32 v111, v125, v167
	v_mul_f32_e32 v96, v111, v111
	s_nop 1
	v_add_f32_dpp v96, v96, v96 quad_perm:[1,0,3,2] row_mask:0xf bank_mask:0xf
	s_nop 1
	v_add_f32_dpp v96, v96, v96 quad_perm:[2,3,0,1] row_mask:0xf bank_mask:0xf
	s_nop 1
	v_add_f32_dpp v96, v96, v96 row_ror:12 row_mask:0xf bank_mask:0xf
	s_nop 1
	v_add_f32_dpp v96, v96, v96 row_ror:8 row_mask:0xf bank_mask:0xf
	v_lshlrev_b32_e32 v115, 3, v158
	v_lshl_add_u32 v115, v115, 2, v113
	s_and_saveexec_b64 s[2:3], s[0:1]
	s_cbranch_execz .LBB0_1075
	s_waitcnt lgkmcnt(0)
	ds_write_b32 v115, v96 offset:61440
.LBB0_1075:
	s_or_b64 exec, exec, s[2:3]
	s_waitcnt lgkmcnt(0)
	ds_read_b32 v117, v113 offset:47876
	v_or_b32_e32 v96, 1, v97
	v_lshl_add_u32 v121, v96, 9, 0
	v_lshl_add_u32 v104, v104, 2, v121
	s_movk_i32 s2, 0xfe20
	v_mad_i32_i24 v121, v96, s2, v121
	ds_read_b32 v123, v104 offset:61696
	ds_read_b128 v[158:161], v121 offset:48192
	s_waitcnt lgkmcnt(2)
	v_mul_f32_e32 v104, 0x3fb8aa3b, v117
	v_exp_f32_e32 v117, v104
	ds_read_b128 v[162:165], v121 offset:48208
	s_waitcnt lgkmcnt(1)
	v_mul_f32_e32 v104, v126, v158
	v_fmac_f32_e32 v104, v117, v123
	v_fmac_f32_e32 v104, v127, v159
	v_fmac_f32_e32 v104, v100, v160
	v_fmac_f32_e32 v104, v101, v161
	s_waitcnt lgkmcnt(0)
	v_fmac_f32_e32 v104, v98, v162
	v_fmac_f32_e32 v104, v99, v163
	v_fmac_f32_e32 v104, v124, v164
	v_fmac_f32_e32 v104, v125, v165
	v_mul_f32_e32 v98, v104, v104
	s_nop 1
	v_add_f32_dpp v98, v98, v98 quad_perm:[1,0,3,2] row_mask:0xf bank_mask:0xf
	s_nop 1
	v_add_f32_dpp v98, v98, v98 quad_perm:[2,3,0,1] row_mask:0xf bank_mask:0xf
	s_nop 1
	v_add_f32_dpp v98, v98, v98 row_ror:12 row_mask:0xf bank_mask:0xf
	s_nop 1
	v_add_f32_dpp v98, v98, v98 row_ror:8 row_mask:0xf bank_mask:0xf
	s_and_saveexec_b64 s[2:3], s[0:1]
	s_cbranch_execz .LBB0_1077
	s_waitcnt lgkmcnt(0)
	ds_write_b32 v115, v98 offset:61444

.LBB0_1181:
	ds_read_b128 v[88:91], v176
	ds_read_b128 v[92:95], v176 offset:64
	v_mov_b64_e32 v[106:107], v[2:3]
	v_mov_b64_e32 v[104:105], v[0:1]
	v_mov_b64_e32 v[122:123], v[6:7]
	s_waitcnt lgkmcnt(1)
	v_mfma_f32_16x16x32_bf16 v[96:99], v[40:43], v[88:91], 0
	v_mov_b64_e32 v[120:121], v[4:5]
	s_ashr_i32 s31, s30, 31
	s_lshl_b64 s[0:1], s[30:31], 14
	v_mfma_f32_16x16x32_bf16 v[88:91], v[48:51], v[88:91], 0
	s_and_b32 s27, s25, 0x1000
	s_add_u32 s0, s7, s0
	s_addc_u32 s1, s19, s1
	s_waitcnt lgkmcnt(0)
	v_mfma_f32_16x16x32_bf16 v[96:99], v[28:31], v[92:95], v[96:99]
	v_lshlrev_b32_e32 v130, 1, v175
	v_mov_b32_e32 v244, v139
	v_mov_b32_e32 v139, v131
	v_mfma_f32_16x16x32_bf16 v[88:91], v[24:27], v[92:95], v[88:91]
	ds_read_b128 v[92:95], v176 offset:128
	ds_read_b128 v[100:103], v176 offset:192
	ds_read_b128 v[0:3], v176 offset:4416
	s_ashr_i32 s29, s28, 31
	s_waitcnt lgkmcnt(2)
	v_mfma_f32_16x16x32_bf16 v[96:99], v[20:23], v[92:95], v[96:99]
	v_mov_b32_e32 v243, v193
	v_mov_b32_e32 v245, v192
	v_add_u32_e32 v209, s23, v205
	v_mfma_f32_16x16x32_bf16 v[88:91], v[16:19], v[92:95], v[88:91]
	ds_read_b128 v[92:95], v176 offset:4352
	v_mov_b32_e32 v242, v194
	s_waitcnt lgkmcnt(2)
	v_mfma_f32_16x16x32_bf16 v[108:111], v[12:15], v[100:103], v[88:91]
	s_waitcnt lgkmcnt(0)
	v_mfma_f32_16x16x32_bf16 v[88:91], v[40:43], v[92:95], 0
	v_mfma_f32_16x16x32_bf16 v[92:95], v[48:51], v[92:95], 0
	v_mfma_f32_16x16x32_bf16 v[124:127], v[8:11], v[100:103], v[96:99]
	ds_read_b128 v[4:7], v176 offset:4480
	s_nop 1
	ds_read_b128 v[96:99], v176 offset:4544
	ds_read_b128 v[100:103], v176 offset:8704
	ds_read_b128 v[116:119], v176 offset:8768
	ds_read_b128 v[210:213], v176 offset:8832
	ds_read_b128 v[214:217], v176 offset:8896
	ds_read_b128 v[218:221], v176 offset:13056
	ds_read_b128 v[222:225], v176 offset:13120
	ds_read_b128 v[226:229], v176 offset:13184
	ds_read_b128 v[230:233], v176 offset:13248
	v_mfma_f32_16x16x32_bf16 v[88:91], v[28:31], v[0:3], v[88:91]
	v_mfma_f32_16x16x32_bf16 v[0:3], v[24:27], v[0:3], v[92:95]
	s_waitcnt lgkmcnt(9)
	v_mfma_f32_16x16x32_bf16 v[0:3], v[16:19], v[4:7], v[0:3]
	s_nop 0
	v_lshl_add_u64 v[92:93], s[0:1], 0, v[142:143]
	v_mfma_f32_16x16x32_bf16 v[88:91], v[20:23], v[4:7], v[88:91]
	v_lshl_add_u64 v[4:5], v[92:93], 0, v[130:131]
	v_lshl_add_u64 v[4:5], v[4:5], 0, v[138:139]
	s_waitcnt lgkmcnt(8)
	v_mfma_f32_16x16x32_bf16 v[112:115], v[12:15], v[96:99], v[0:3]
	s_waitcnt lgkmcnt(7)
	v_mfma_f32_16x16x32_bf16 v[0:3], v[40:43], v[100:103], 0
	v_mfma_f32_16x16x32_bf16 v[234:237], v[8:11], v[96:99], v[88:91]
	s_nop 2
	v_add_u32_e32 v90, s27, v174
	s_waitcnt lgkmcnt(6)
	v_mfma_f32_16x16x32_bf16 v[0:3], v[28:31], v[116:119], v[0:3]
	v_readfirstlane_b32 s27, v90
	s_mov_b32 m0, s27
	v_add_u32_e32 v91, 0x800, v90
	global_load_lds_dwordx4 v[4:5], off
	v_add_u32_e32 v4, s23, v208
	v_ashrrev_i32_e32 v5, 31, v4
	v_lshlrev_b64 v[88:89], 13, v[4:5]
	v_readfirstlane_b32 s27, v91
	v_lshl_add_u64 v[88:89], v[140:141], 0, v[88:89]
	s_mov_b32 m0, s27
	v_add_u32_e32 v91, 0x400, v90
	global_load_lds_dwordx4 v[88:89], off
	v_lshl_add_u64 v[88:89], s[0:1], 0, v[144:145]
	s_waitcnt lgkmcnt(0)
	v_mfma_f32_16x16x32_bf16 v[0:3], v[20:23], v[210:213], v[0:3]
	v_lshl_add_u64 v[88:89], v[88:89], 0, v[130:131]
	v_readfirstlane_b32 s0, v91
	v_lshl_add_u64 v[88:89], v[88:89], 0, v[138:139]
	s_mov_b32 m0, s0
	v_mfma_f32_16x16x32_bf16 v[238:241], v[8:11], v[214:217], v[0:3]
	global_load_lds_dwordx4 v[88:89], off
	v_add_u32_e32 v88, s23, v207
	v_ashrrev_i32_e32 v89, 31, v88
	v_add_u32_e32 v2, 0xc00, v90
	v_mfma_f32_16x16x32_bf16 v[4:7], v[48:51], v[100:103], 0
	v_lshlrev_b64 v[88:89], 13, v[88:89]
	v_readfirstlane_b32 s0, v2
	v_lshl_add_u64 v[0:1], v[140:141], 0, v[88:89]
	s_mov_b32 m0, s0
	v_mfma_f32_16x16x32_bf16 v[4:7], v[24:27], v[116:119], v[4:7]
	global_load_lds_dwordx4 v[0:1], off
	s_ashr_i32 s27, s26, 31
	v_mfma_f32_16x16x32_bf16 v[0:3], v[40:43], v[218:221], 0
	s_lshl_b64 s[0:1], s[28:29], 13
	s_lshl_b64 s[48:49], s[26:27], 14
	v_mfma_f32_16x16x32_bf16 v[40:43], v[48:51], v[218:221], 0
	v_lshl_add_u64 v[48:49], v[150:151], 0, s[48:49]
	v_add_u32_e32 v220, 0x82, v209
	v_ashrrev_i32_e32 v221, 31, v220
	v_mfma_f32_16x16x32_bf16 v[28:31], v[28:31], v[222:225], v[0:3]
	v_lshlrev_b64 v[220:221], 7, v[220:221]
	v_lshl_add_u64 v[220:221], s[14:15], 0, v[220:221]
	v_mfma_f32_16x16x32_bf16 v[24:27], v[24:27], v[222:225], v[40:43]
	v_add_u32_e32 v222, 0x83, v209
	v_ashrrev_i32_e32 v223, 31, v222
	v_lshlrev_b64 v[222:223], 7, v[222:223]
	v_mfma_f32_16x16x32_bf16 v[4:7], v[16:19], v[210:213], v[4:7]
	v_lshl_add_u64 v[222:223], s[14:15], 0, v[222:223]
	v_mfma_f32_16x16x32_bf16 v[20:23], v[20:23], v[226:229], v[28:31]
	s_nop 2
	v_add_u32_e32 v28, s23, v206
	v_mfma_f32_16x16x32_bf16 v[16:19], v[16:19], v[226:229], v[24:27]
	v_ashrrev_i32_e32 v29, 31, v28
	v_lshlrev_b64 v[28:29], 12, v[28:29]
	v_lshl_add_u64 v[210:211], v[154:155], 0, v[28:29]
	v_mfma_f32_16x16x32_bf16 v[116:119], v[12:15], v[214:217], v[4:7]
	v_mul_f32_e32 v229, 0x3fb8aa3b, v243
	v_exp_f32_e32 v229, v229
	s_nop 0
	v_lshl_add_u64 v[4:5], v[148:149], 0, s[0:1]
	s_lshl_b64 s[0:1], s[28:29], 14
	v_lshl_add_u64 v[192:193], v[152:153], 0, s[0:1]
	global_load_dwordx4 v[0:3], v[4:5], off
	s_nop 0
	global_load_dwordx4 v[4:7], v[4:5], off offset:64
	s_nop 0
	global_load_dwordx4 v[100:103], v[48:49], off
	global_load_dwordx4 v[96:99], v[48:49], off offset:64
	global_load_dwordx4 v[92:95], v[48:49], off offset:2048
	global_load_dwordx4 v[88:91], v[48:49], off offset:2112
	global_load_dwordx4 v[40:43], v[192:193], off
	global_load_dwordx4 v[28:31], v[192:193], off offset:64
	v_mfma_f32_16x16x32_bf16 v[212:215], v[8:11], v[230:233], v[20:23]
	global_load_dwordx4 v[48:51], v[210:211], off
	global_load_dwordx4 v[24:27], v[210:211], off offset:64
	s_nop 0
	global_load_dwordx4 v[20:23], v[192:193], off offset:128
	global_load_dwordx4 v[8:11], v[192:193], off offset:192
	v_add_u32_e32 v192, 0x80, v209
	v_ashrrev_i32_e32 v193, 31, v192
	v_mfma_f32_16x16x32_bf16 v[216:219], v[12:15], v[230:233], v[16:19]
	s_nop 2
	global_load_dwordx4 v[16:19], v[210:211], off offset:128
	global_load_dwordx4 v[12:15], v[210:211], off offset:192
	v_add_u32_e32 v210, 0x81, v209
	v_ashrrev_i32_e32 v211, 31, v210
	v_lshlrev_b64 v[192:193], 7, v[192:193]
	v_lshlrev_b64 v[210:211], 7, v[210:211]
	s_add_i32 s0, s25, 0xfffff000
	v_lshl_add_u64 v[192:193], s[14:15], 0, v[192:193]
	v_lshl_add_u64 v[210:211], s[14:15], 0, v[210:211]
	s_and_b32 s0, s0, 0x1000
	global_load_dword v194, v[192:193], off
	s_nop 0
	global_load_dword v193, v[210:211], off
	global_load_dword v139, v[220:221], off
	global_load_dword v192, v[222:223], off
	global_load_dword v130, v131, s[34:35]
	v_add_u32_e32 v210, s0, v174
	v_add_u32_e32 v211, v210, v195
	v_add3_u32 v211, v211, v196, v197
	ds_read2st64_b64 v[220:223], v211 offset1:1
	ds_read2st64_b64 v[224:227], v211 offset0:2 offset1:3
	v_mul_f32_e32 v211, 0x3fb8aa3b, v242
	v_sub_f32_e32 v230, v204, v243
	v_exp_f32_e32 v228, v211
	s_waitcnt lgkmcnt(0)
	v_lshlrev_b32_e32 v243, 16, v220
	v_sub_f32_e32 v211, v204, v242
	v_mul_f32_e32 v230, 0x3fb8aa3b, v230
	v_sub_f32_e32 v243, v243, v124
	v_and_b32_e32 v124, 0xffff0000, v220
	v_mul_f32_e32 v211, 0x3fb8aa3b, v211
	v_exp_f32_e32 v232, v230
	v_mul_f32_e32 v230, 0x3fb8aa3b, v244
	v_sub_f32_e32 v231, v204, v244
	v_sub_f32_e32 v242, v204, v245
	v_sub_f32_e32 v244, v124, v125
	v_alignbit_b32 v124, v221, v220, 16
	v_exp_f32_e32 v211, v211
	v_mul_f32_e32 v231, 0x3fb8aa3b, v231
	v_mul_f32_e32 v242, 0x3fb8aa3b, v242
	v_and_b32_e32 v124, 0xffff0000, v124
	v_exp_f32_e32 v233, v231
	v_exp_f32_e32 v242, v242
	v_sub_f32_e32 v126, v124, v126
	v_and_b32_e32 v124, 0xffff0000, v221
	v_sub_f32_e32 v127, v124, v127
	v_cvt_pk_bf16_f32 v124, v243, v244
	v_cvt_pk_bf16_f32 v125, v126, v127
	ds_write_b64 v178, v[124:125] offset:34816
	v_mul_f32_e32 v124, v211, v243
	v_mul_f32_e32 v125, v232, v244
	v_cvt_pk_bf16_f32 v124, v124, v125
	v_mul_f32_e32 v125, v233, v126
	v_mul_f32_e32 v126, v242, v127
	v_cvt_pk_bf16_f32 v125, v125, v126
	ds_write_b64 v178, v[124:125] offset:53248
	v_lshlrev_b32_e32 v124, 16, v222
	v_sub_f32_e32 v126, v124, v234
	v_and_b32_e32 v124, 0xffff0000, v222
	v_sub_f32_e32 v127, v124, v235
	v_alignbit_b32 v124, v223, v222, 16
	v_and_b32_e32 v124, 0xffff0000, v124
	v_sub_f32_e32 v220, v124, v236
	v_and_b32_e32 v124, 0xffff0000, v223
	v_sub_f32_e32 v221, v124, v237
	v_cvt_pk_bf16_f32 v124, v126, v127
	v_cvt_pk_bf16_f32 v125, v220, v221
	ds_write_b64 v178, v[124:125] offset:37120
	v_mul_f32_e32 v124, v211, v126
	v_mul_f32_e32 v125, v232, v127
	v_cvt_pk_bf16_f32 v124, v124, v125
	v_mul_f32_e32 v125, v233, v220
	v_mul_f32_e32 v126, v242, v221
	v_cvt_pk_bf16_f32 v125, v125, v126
	ds_write_b64 v178, v[124:125] offset:55552
	v_lshlrev_b32_e32 v124, 16, v224
	v_sub_f32_e32 v126, v124, v238
	v_and_b32_e32 v124, 0xffff0000, v224
	v_sub_f32_e32 v127, v124, v239
	v_alignbit_b32 v124, v225, v224, 16
	v_and_b32_e32 v124, 0xffff0000, v124
	v_sub_f32_e32 v220, v124, v240
	v_and_b32_e32 v124, 0xffff0000, v225
	v_sub_f32_e32 v221, v124, v241
	v_cvt_pk_bf16_f32 v124, v126, v127
	v_cvt_pk_bf16_f32 v125, v220, v221
	ds_write_b64 v178, v[124:125] offset:39424
	v_mul_f32_e32 v124, v211, v126
	v_mul_f32_e32 v125, v232, v127
	v_cvt_pk_bf16_f32 v124, v124, v125
	v_mul_f32_e32 v125, v233, v220
	v_mul_f32_e32 v126, v242, v221
	v_cvt_pk_bf16_f32 v125, v125, v126
	ds_write_b64 v178, v[124:125] offset:57856
	v_lshlrev_b32_e32 v124, 16, v226
	v_sub_f32_e32 v126, v124, v212
	v_and_b32_e32 v124, 0xffff0000, v226
	v_sub_f32_e32 v127, v124, v213
	v_alignbit_b32 v124, v227, v226, 16
	v_and_b32_e32 v124, 0xffff0000, v124
	v_sub_f32_e32 v212, v124, v214
	v_and_b32_e32 v124, 0xffff0000, v227
	v_sub_f32_e32 v213, v124, v215
	v_cvt_pk_bf16_f32 v124, v126, v127
	v_cvt_pk_bf16_f32 v125, v212, v213
	ds_write_b64 v178, v[124:125] offset:41728
	v_mul_f32_e32 v124, v211, v126
	v_mul_f32_e32 v125, v232, v127
	v_cvt_pk_bf16_f32 v124, v124, v125
	v_mul_f32_e32 v125, v233, v212
	v_mul_f32_e32 v126, v242, v213
	v_cvt_pk_bf16_f32 v125, v125, v126
	ds_write_b64 v178, v[124:125] offset:60160
	v_mul_f32_e32 v231, 0x3fb8aa3b, v245
	s_waitcnt lgkmcnt(0)
	s_barrier
	v_exp_f32_e32 v230, v230
	v_exp_f32_e32 v231, v231
	ds_read_b128 v[124:127], v180 offset:34816
	ds_read_b128 v[212:215], v180 offset:34880
	v_pk_mul_f32 v[108:109], v[228:229], v[108:109]
	v_pk_mul_f32 v[110:111], v[230:231], v[110:111]
	v_pk_mul_f32 v[112:113], v[228:229], v[112:113]
	v_pk_mul_f32 v[114:115], v[230:231], v[114:115]
	s_waitcnt lgkmcnt(0)
	v_mfma_f32_16x16x32_bf16 v[108:111], v[104:107], v[124:127], v[108:111]
	ds_read_b128 v[124:127], v180 offset:37120
	v_pk_mul_f32 v[116:117], v[228:229], v[116:117]
	v_pk_mul_f32 v[118:119], v[230:231], v[118:119]
	v_mfma_f32_16x16x32_bf16 v[108:111], v[120:123], v[212:215], v[108:111]
	ds_read_b128 v[212:215], v180 offset:37184
	s_waitcnt lgkmcnt(0)
	v_mfma_f32_16x16x32_bf16 v[112:115], v[104:107], v[124:127], v[112:115]
	ds_read_b128 v[124:127], v180 offset:39424
	v_mfma_f32_16x16x32_bf16 v[112:115], v[120:123], v[212:215], v[112:115]
	ds_read_b128 v[212:215], v180 offset:39488
	s_waitcnt lgkmcnt(0)
	v_mfma_f32_16x16x32_bf16 v[116:119], v[104:107], v[124:127], v[116:119]
	ds_read_b128 v[124:127], v180 offset:41728
	v_mfma_f32_16x16x32_bf16 v[116:119], v[120:123], v[212:215], v[116:119]
	v_mul_f32_e64 v212, v228, v216
	v_mul_f32_e64 v213, v229, v217
	v_pk_mul_f32 v[214:215], v[230:231], v[218:219]
	ds_read_b128 v[216:219], v180 offset:41792
	s_waitcnt lgkmcnt(0)
	v_mfma_f32_16x16x32_bf16 v[104:107], v[104:107], v[124:127], v[212:215]
	v_mfma_f32_16x16x32_bf16 v[104:107], v[120:123], v[216:219], v[104:107]
	v_mul_f32_e64 v120, v114, v114
	v_mul_f32_e64 v121, v115, v115
	v_pk_mul_f32 v[122:123], v[112:113], v[112:113]
	v_pk_fma_f32 v[120:121], v[110:111], v[110:111], v[120:121]
	v_pk_fma_f32 v[122:123], v[108:109], v[108:109], v[122:123]
	v_pk_fma_f32 v[120:121], v[118:119], v[118:119], v[120:121]
	v_pk_fma_f32 v[122:123], v[116:117], v[116:117], v[122:123]
	s_nop 0
	v_pk_fma_f32 v[120:121], v[106:107], v[106:107], v[120:121]
	v_pk_fma_f32 v[122:123], v[104:105], v[104:105], v[122:123]
	s_nop 1
	v_add_f32_dpp v120, v120, v120 quad_perm:[1,0,3,2] row_mask:0xf bank_mask:0xf
	v_add_f32_dpp v121, v121, v121 quad_perm:[1,0,3,2] row_mask:0xf bank_mask:0xf
	v_add_f32_dpp v122, v122, v122 quad_perm:[1,0,3,2] row_mask:0xf bank_mask:0xf
	v_add_f32_dpp v123, v123, v123 quad_perm:[1,0,3,2] row_mask:0xf bank_mask:0xf
	v_add_f32_dpp v120, v120, v120 quad_perm:[2,3,0,1] row_mask:0xf bank_mask:0xf
	v_add_f32_dpp v121, v121, v121 quad_perm:[2,3,0,1] row_mask:0xf bank_mask:0xf
	v_add_f32_dpp v122, v122, v122 quad_perm:[2,3,0,1] row_mask:0xf bank_mask:0xf
	v_add_f32_dpp v123, v123, v123 quad_perm:[2,3,0,1] row_mask:0xf bank_mask:0xf
	v_add_f32_dpp v120, v120, v120 row_ror:12 row_mask:0xf bank_mask:0xf
	v_add_f32_dpp v121, v121, v121 row_ror:12 row_mask:0xf bank_mask:0xf
	v_add_f32_dpp v122, v122, v122 row_ror:12 row_mask:0xf bank_mask:0xf
	v_add_f32_dpp v123, v123, v123 row_ror:12 row_mask:0xf bank_mask:0xf
	v_add_f32_dpp v120, v120, v120 row_ror:8 row_mask:0xf bank_mask:0xf
	v_add_f32_dpp v121, v121, v121 row_ror:8 row_mask:0xf bank_mask:0xf
	v_add_f32_dpp v122, v122, v122 row_ror:8 row_mask:0xf bank_mask:0xf
	v_add_f32_dpp v123, v123, v123 row_ror:8 row_mask:0xf bank_mask:0xf
	s_and_saveexec_b64 s[0:1], vcc
	s_cbranch_execz .LBB0_1183
	ds_write2_b32 v198, v122, v123 offset1:1
	ds_write2_b32 v198, v120, v121 offset0:2 offset1:3
.LBB0_1183:
	s_or_b64 exec, exec, s[0:1]
	v_mul_f32_e32 v120, 0x3fb8aa3b, v204
	v_exp_f32_e32 v204, v120
	s_waitcnt lgkmcnt(0)
	ds_read_b128 v[120:123], v188 offset:53248
	ds_read_b128 v[124:127], v188 offset:53312
	ds_read_b128 v[212:215], v191 offset:53248
	ds_read_b128 v[216:219], v191 offset:53312
	ds_read_b128 v[220:223], v189 offset:53248
	ds_read_b128 v[224:227], v189 offset:53312
	v_pk_mul_f32 v[54:55], v[54:55], v[204:205] op_sel_hi:[1,0]
	v_pk_mul_f32 v[52:53], v[52:53], v[204:205] op_sel_hi:[1,0]
	v_pk_mul_f32 v[58:59], v[58:59], v[204:205] op_sel_hi:[1,0]
	v_pk_mul_f32 v[56:57], v[56:57], v[204:205] op_sel_hi:[1,0]
	s_waitcnt lgkmcnt(0)
	v_mfma_f32_16x16x32_bf16 v[52:55], v[80:83], v[120:123], v[52:55]
	v_mul_f32_e64 v46, v46, v204
	v_mul_f32_e64 v47, v47, v204
	v_pk_mul_f32 v[44:45], v[44:45], v[204:205] op_sel_hi:[1,0]
	v_pk_mul_f32 v[38:39], v[38:39], v[204:205] op_sel_hi:[1,0]
	v_pk_mul_f32 v[36:37], v[36:37], v[204:205] op_sel_hi:[1,0]
	ds_read_b128 v[228:231], v187 offset:53248
	ds_read_b128 v[232:235], v187 offset:53312
	v_add_u32_e32 v255, v210, v199
	v_add3_u32 v255, v255, v200, v201
	ds_read_u16 v236, v255 offset:2048
	ds_read_u16 v237, v255 offset:2080
	ds_read_u16 v238, v255 offset:2112
	ds_read_u16 v239, v255 offset:2144
	ds_read_u16 v240, v255 offset:2176
	ds_read_u16 v241, v255 offset:2208
	ds_read_u16 v242, v255 offset:2240
	ds_read_u16 v243, v255 offset:2272
	ds_read_u16 v244, v255 offset:2304
	ds_read_u16 v245, v255 offset:2336
	ds_read_u16 v249, v255 offset:2368
	ds_read_u16 v250, v255 offset:2400
	ds_read_u16 v251, v255 offset:2432
	ds_read_u16 v252, v255 offset:2464
	ds_read_u16 v253, v255 offset:2496
	ds_read_u16 v254, v255 offset:2528
	v_pk_mul_f32 v[62:63], v[62:63], v[204:205] op_sel_hi:[1,0]
	v_pk_mul_f32 v[60:61], v[60:61], v[204:205] op_sel_hi:[1,0]
	v_pk_mul_f32 v[66:67], v[66:67], v[204:205] op_sel_hi:[1,0]
	v_pk_mul_f32 v[64:65], v[64:65], v[204:205] op_sel_hi:[1,0]
	v_mfma_f32_16x16x32_bf16 v[56:59], v[72:75], v[120:123], v[56:59]
	v_mul_f32_e64 v34, v34, v204
	v_mul_f32_e64 v35, v35, v204
	v_pk_mul_f32 v[32:33], v[32:33], v[204:205] op_sel_hi:[1,0]
	v_pk_mul_f32 v[70:71], v[70:71], v[204:205] op_sel_hi:[1,0]
	v_mfma_f32_16x16x32_bf16 v[44:47], v[80:83], v[212:215], v[44:47]
	v_mul_f32_e64 v68, v68, v204
	v_mul_f32_e64 v69, v69, v204
	s_waitcnt lgkmcnt(0)
	s_barrier
	v_mfma_f32_16x16x32_bf16 v[36:39], v[80:83], v[220:223], v[36:39]
	v_lshlrev_b32_e32 v236, 16, v236
	v_lshlrev_b32_e32 v237, 16, v237
	v_lshlrev_b32_e32 v238, 16, v238
	v_lshlrev_b32_e32 v239, 16, v239
	v_lshlrev_b32_e32 v240, 16, v240
	v_lshlrev_b32_e32 v241, 16, v241
	v_lshlrev_b32_e32 v242, 16, v242
	v_lshlrev_b32_e32 v243, 16, v243
	s_add_i32 s23, s23, 64
	s_addk_i32 s25, 0x1000
	v_mfma_f32_16x16x32_bf16 v[60:63], v[72:75], v[212:215], v[60:63]
	v_lshlrev_b32_e32 v244, 16, v244
	v_lshlrev_b32_e32 v245, 16, v245
	v_lshlrev_b32_e32 v249, 16, v249
	v_lshlrev_b32_e32 v250, 16, v250
	v_lshlrev_b32_e32 v251, 16, v251
	v_lshlrev_b32_e32 v252, 16, v252
	v_lshlrev_b32_e32 v253, 16, v253
	v_lshlrev_b32_e32 v254, 16, v254
	s_add_i32 s30, s30, 32
	s_add_i32 s26, s26, 16
	s_add_i32 s28, s28, 32
	v_mfma_f32_16x16x32_bf16 v[64:67], v[72:75], v[220:223], v[64:67]
	s_add_u32 s34, s34, 0x2000
	s_addc_u32 s35, s35, 0
	s_cmpk_eq_i32 s23, 0x780
	v_mfma_f32_16x16x32_bf16 v[52:55], v[84:87], v[124:127], v[52:55]
	v_mul_f32_e32 v212, 0xbfb8aa3b, v236
	v_mul_f32_e32 v213, 0xbfb8aa3b, v237
	v_mul_f32_e32 v214, 0xbfb8aa3b, v238
	v_mul_f32_e32 v215, 0xbfb8aa3b, v239
	v_mul_f32_e32 v220, 0xbfb8aa3b, v240
	v_mul_f32_e32 v221, 0xbfb8aa3b, v241
	v_mul_f32_e32 v222, 0xbfb8aa3b, v242
	v_mul_f32_e32 v223, 0xbfb8aa3b, v243
	v_mfma_f32_16x16x32_bf16 v[56:59], v[76:79], v[124:127], v[56:59]
	v_exp_f32_e32 v212, v212
	v_exp_f32_e32 v213, v213
	v_exp_f32_e32 v214, v214
	v_exp_f32_e32 v215, v215
	v_exp_f32_e32 v220, v220
	v_exp_f32_e32 v221, v221
	v_exp_f32_e32 v222, v222
	v_exp_f32_e32 v223, v223
	v_mfma_f32_16x16x32_bf16 v[44:47], v[84:87], v[216:219], v[44:47]
	v_add_f32_e32 v212, 1.0, v212
	v_add_f32_e32 v213, 1.0, v213
	v_add_f32_e32 v214, 1.0, v214
	v_add_f32_e32 v215, 1.0, v215
	v_add_f32_e32 v220, 1.0, v220
	v_add_f32_e32 v221, 1.0, v221
	v_add_f32_e32 v222, 1.0, v222
	v_add_f32_e32 v223, 1.0, v223
	v_mfma_f32_16x16x32_bf16 v[36:39], v[84:87], v[224:227], v[36:39]
	v_rcp_f32_e32 v212, v212
	v_rcp_f32_e32 v213, v213
	v_rcp_f32_e32 v214, v214
	v_rcp_f32_e32 v215, v215
	v_rcp_f32_e32 v220, v220
	v_rcp_f32_e32 v221, v221
	v_rcp_f32_e32 v222, v222
	v_rcp_f32_e32 v223, v223
	s_nop 5
	v_cvt_pk_bf16_f32 v120, v56, v57
	v_cvt_pk_bf16_f32 v121, v58, v59
	s_waitcnt lgkmcnt(0)
	v_mfma_f32_16x16x32_bf16 v[32:35], v[80:83], v[228:231], v[32:35]
	v_mul_f32_e32 v236, v212, v236
	v_mul_f32_e32 v237, v213, v237
	v_mul_f32_e32 v238, v214, v238
	v_mul_f32_e32 v239, v215, v239
	v_mul_f32_e32 v240, v220, v240
	v_mul_f32_e32 v241, v221, v241
	v_mul_f32_e32 v242, v222, v242
	v_mul_f32_e32 v243, v223, v243
	v_cvt_pk_bf16_f32 v80, v52, v53
	v_cvt_pk_bf16_f32 v81, v54, v55
	v_cvt_pk_bf16_f32 v82, v44, v45
	v_mfma_f32_16x16x32_bf16 v[60:63], v[76:79], v[216:219], v[60:63]
	v_mul_f32_e32 v212, 0xbfb8aa3b, v244
	v_mul_f32_e32 v213, 0xbfb8aa3b, v245
	v_mul_f32_e32 v214, 0xbfb8aa3b, v249
	v_mul_f32_e32 v215, 0xbfb8aa3b, v250
	v_mul_f32_e32 v220, 0xbfb8aa3b, v251
	v_mul_f32_e32 v221, 0xbfb8aa3b, v252
	v_mul_f32_e32 v222, 0xbfb8aa3b, v253
	v_mul_f32_e32 v223, 0xbfb8aa3b, v254
	v_cvt_pk_bf16_f32 v83, v46, v47
	ds_write2_b64 v173, v[80:81], v[120:121] offset1:4
	v_mfma_f32_16x16x32_bf16 v[64:67], v[76:79], v[224:227], v[64:67]
	v_exp_f32_e32 v212, v212
	v_exp_f32_e32 v213, v213
	v_exp_f32_e32 v214, v214
	v_exp_f32_e32 v215, v215
	v_exp_f32_e32 v220, v220
	v_exp_f32_e32 v221, v221
	v_exp_f32_e32 v222, v222
	v_exp_f32_e32 v223, v223
	v_mfma_f32_16x16x32_bf16 v[68:71], v[72:75], v[228:231], v[68:71]
	v_add_f32_e32 v212, 1.0, v212
	v_add_f32_e32 v213, 1.0, v213
	v_add_f32_e32 v214, 1.0, v214
	v_add_f32_e32 v215, 1.0, v215
	v_add_f32_e32 v220, 1.0, v220
	v_add_f32_e32 v221, 1.0, v221
	v_add_f32_e32 v222, 1.0, v222
	v_add_f32_e32 v223, 1.0, v223
	s_nop 3
	v_cvt_pk_bf16_f32 v80, v60, v61
	v_cvt_pk_bf16_f32 v81, v62, v63
	s_nop 0
	v_cvt_pk_bf16_f32 v72, v64, v65
	v_mfma_f32_16x16x32_bf16 v[32:35], v[84:87], v[232:235], v[32:35]
	v_rcp_f32_e32 v212, v212
	v_rcp_f32_e32 v213, v213
	v_rcp_f32_e32 v214, v214
	v_rcp_f32_e32 v215, v215
	v_rcp_f32_e32 v220, v220
	v_rcp_f32_e32 v221, v221
	v_rcp_f32_e32 v222, v222
	v_rcp_f32_e32 v223, v223
	v_cvt_pk_bf16_f32 v84, v36, v37
	v_cvt_pk_bf16_f32 v85, v38, v39
	v_cvt_pk_bf16_f32 v73, v66, v67
	v_mfma_f32_16x16x32_bf16 v[68:71], v[76:79], v[232:235], v[68:71]
	v_mul_f32_e32 v244, v212, v244
	v_mul_f32_e32 v245, v213, v245
	v_mul_f32_e32 v249, v214, v249
	v_mul_f32_e32 v250, v215, v250
	v_mul_f32_e32 v251, v220, v251
	v_mul_f32_e32 v252, v221, v252
	v_mul_f32_e32 v253, v222, v253
	v_mul_f32_e32 v254, v223, v254
	ds_write2_b64 v184, v[82:83], v[80:81] offset0:32 offset1:36
	ds_write2_b64 v185, v[84:85], v[72:73] offset0:64 offset1:68
	v_cvt_pk_bf16_f32 v86, v32, v33
	v_cvt_pk_bf16_f32 v87, v34, v35
	v_cvt_pk_bf16_f32 v72, v68, v69
	v_cvt_pk_bf16_f32 v73, v70, v71
	ds_write2_b64 v186, v[86:87], v[72:73] offset0:96 offset1:100
	ds_read_b128 v[72:75], v179
	ds_read_b128 v[76:79], v179 offset:256
	v_add_u32_e32 v80, 64, v209
	v_ashrrev_i32_e32 v81, 31, v80
	v_lshlrev_b64 v[80:81], 13, v[80:81]
	v_lshl_add_u64 v[80:81], v[156:157], 0, v[80:81]
	v_add_u32_e32 v82, 0x41, v209
	v_ashrrev_i32_e32 v83, 31, v82
	v_lshlrev_b64 v[82:83], 13, v[82:83]
	v_lshl_add_u64 v[82:83], v[156:157], 0, v[82:83]
	v_add_u32_e32 v84, 0x42, v209
	v_ashrrev_i32_e32 v85, 31, v84
	v_lshlrev_b64 v[84:85], 13, v[84:85]
	v_lshl_add_u64 v[84:85], v[156:157], 0, v[84:85]
	v_add_u32_e32 v86, 0x43, v209
	v_ashrrev_i32_e32 v87, 31, v86
	v_lshlrev_b64 v[86:87], 13, v[86:87]
	v_lshl_add_u64 v[86:87], v[156:157], 0, v[86:87]
	s_waitcnt lgkmcnt(0)
	v_pk_add_f32 v[72:73], v[72:73], v[76:77]
	v_pk_add_f32 v[74:75], v[74:75], v[78:79]
	v_mov_b64_e32 v[76:77], s[20:21]
	v_pk_fma_f32 v[72:73], v[72:73], s[18:19], v[76:77] op_sel_hi:[1,0,0]
	v_pk_fma_f32 v[74:75], v[74:75], s[18:19], v[76:77] op_sel_hi:[1,0,0]
	v_cmp_gt_f32_e64 s[0:1], s45, v72
	v_cmp_gt_f32_e64 s[98:99], s45, v73
	v_cmp_gt_f32_e64 s[100:101], s45, v74
	v_mul_f32_e32 v120, 0x4b800000, v72
	v_mul_f32_e32 v121, 0x4b800000, v73
	v_mul_f32_e32 v122, 0x4b800000, v74
	v_mul_f32_e32 v123, 0x4b800000, v75
	v_cndmask_b32_e64 v72, v72, v120, s[0:1]
	v_cndmask_b32_e64 v73, v73, v121, s[98:99]
	v_cndmask_b32_e64 v74, v74, v122, s[100:101]
	v_rsq_f32_e32 v72, v72
	v_rsq_f32_e32 v73, v73
	v_rsq_f32_e32 v74, v74
	s_nop 0
	v_mul_f32_e32 v120, 0x45800000, v72
	v_mul_f32_e32 v121, 0x45800000, v73
	v_mul_f32_e32 v122, 0x45800000, v74
	v_cndmask_b32_e64 v72, v72, v120, s[0:1]
	v_cndmask_b32_e64 v73, v73, v121, s[98:99]
	v_cndmask_b32_e64 v74, v74, v122, s[100:101]
	v_cmp_gt_f32_e64 s[0:1], s45, v75
	s_nop 0
	v_cndmask_b32_e64 v75, v75, v123, s[0:1]
	v_rsq_f32_e32 v75, v75
	v_mul_f32_e32 v120, v108, v72
	v_mul_f32_e32 v121, v112, v72
	v_mul_f32_e32 v122, v116, v72
	v_mul_f32_e32 v123, v104, v72
	v_mul_f32_e32 v120, v172, v120
	v_mul_f32_e32 v121, v171, v121
	v_mul_f32_e32 v122, v170, v122
	v_mul_f32_e32 v123, v169, v123
	v_mul_f32_e32 v120, v236, v120
	v_mul_f32_e32 v121, v237, v121
	v_mul_f32_e32 v122, v238, v122
	v_mul_f32_e32 v123, v239, v123
	v_cvt_pk_bf16_f32 v120, v120, s0
	v_cvt_pk_bf16_f32 v121, v121, s0
	v_cvt_pk_bf16_f32 v122, v122, s0
	v_cvt_pk_bf16_f32 v123, v123, s0
	global_store_short v[80:81], v120, off
	global_store_short v[80:81], v121, off offset:32
	global_store_short v[80:81], v122, off offset:64
	global_store_short v[80:81], v123, off offset:96
	v_mul_f32_e32 v124, 0x45800000, v75
	v_cndmask_b32_e64 v75, v75, v124, s[0:1]
	v_mul_f32_e32 v120, v109, v73
	v_mul_f32_e32 v121, v113, v73
	v_mul_f32_e32 v122, v117, v73
	v_mul_f32_e32 v123, v105, v73
	v_mul_f32_e32 v120, v172, v120
	v_mul_f32_e32 v121, v171, v121
	v_mul_f32_e32 v122, v170, v122
	v_mul_f32_e32 v123, v169, v123
	v_mul_f32_e32 v120, v240, v120
	v_mul_f32_e32 v121, v241, v121
	v_mul_f32_e32 v122, v242, v122
	v_mul_f32_e32 v123, v243, v123
	v_cvt_pk_bf16_f32 v120, v120, s0
	v_cvt_pk_bf16_f32 v121, v121, s0
	v_cvt_pk_bf16_f32 v122, v122, s0
	v_cvt_pk_bf16_f32 v123, v123, s0
	global_store_short v[82:83], v120, off
	global_store_short v[82:83], v121, off offset:32
	global_store_short v[82:83], v122, off offset:64
	global_store_short v[82:83], v123, off offset:96
	v_mul_f32_e32 v120, v110, v74
	v_mul_f32_e32 v121, v114, v74
	v_mul_f32_e32 v122, v118, v74
	v_mul_f32_e32 v123, v106, v74
	v_mul_f32_e32 v120, v172, v120
	v_mul_f32_e32 v121, v171, v121
	v_mul_f32_e32 v122, v170, v122
	v_mul_f32_e32 v123, v169, v123
	v_mul_f32_e32 v120, v244, v120
	v_mul_f32_e32 v121, v245, v121
	v_mul_f32_e32 v122, v249, v122
	v_mul_f32_e32 v123, v250, v123
	v_cvt_pk_bf16_f32 v120, v120, s0
	v_cvt_pk_bf16_f32 v121, v121, s0
	v_cvt_pk_bf16_f32 v122, v122, s0
	v_cvt_pk_bf16_f32 v123, v123, s0
	global_store_short v[84:85], v120, off
	global_store_short v[84:85], v121, off offset:32
	global_store_short v[84:85], v122, off offset:64
	global_store_short v[84:85], v123, off offset:96
	v_mul_f32_e32 v120, v111, v75
	v_mul_f32_e32 v121, v115, v75
	v_mul_f32_e32 v122, v119, v75
	v_mul_f32_e32 v123, v107, v75
	v_mul_f32_e32 v120, v172, v120
	v_mul_f32_e32 v121, v171, v121
	v_mul_f32_e32 v122, v170, v122
	v_mul_f32_e32 v123, v169, v123
	v_mul_f32_e32 v120, v251, v120
	v_mul_f32_e32 v121, v252, v121
	v_mul_f32_e32 v122, v253, v122
	v_mul_f32_e32 v123, v254, v123
	v_cvt_pk_bf16_f32 v120, v120, s0
	v_cvt_pk_bf16_f32 v121, v121, s0
	v_cvt_pk_bf16_f32 v122, v122, s0
	v_cvt_pk_bf16_f32 v123, v123, s0
	global_store_short v[86:87], v120, off
	global_store_short v[86:87], v121, off offset:32
	global_store_short v[86:87], v122, off offset:64
	global_store_short v[86:87], v123, off offset:96
	s_waitcnt lgkmcnt(0)
	s_barrier
	s_cbranch_scc1 .LBB0_1185
	s_waitcnt vmcnt(0)
	v_mov_b64_e32 v[76:77], v[88:89]
	v_mov_b64_e32 v[72:73], v[92:93]
	v_mov_b64_e32 v[84:85], v[96:97]
	v_mov_b64_e32 v[80:81], v[100:101]
	v_mov_b64_e32 v[78:79], v[90:91]
	v_mov_b64_e32 v[74:75], v[94:95]
	v_mov_b64_e32 v[86:87], v[98:99]
	v_mov_b64_e32 v[82:83], v[102:103]
	v_mov_b32_e32 v204, v130
	s_branch .LBB0_1181
